# PH2 prompt pooling: window sums under exec masks (w>=4, w>=8, w==16) with wave-uniform skips instead of 15 adds + selects per row; same per-lane add order
# speedup vs baseline: 1.0054x; 1.0054x over previous
; __device__ __forceinline__ unsigned cvt_pk_bf16(float lo, float hi) { unsigned r; asm volatile("v_cvt_pk_bf16_f32 %0, %1, %2" : "=v"(r) : "v"(lo), "v"(hi)); return r; }
; __global__ void __launch_bounds__(512, 2) fwd_kernel(Args a) {
;     ...
;             for (int j = 0; j < 8; ++j) {
;                 const int tl = tl0 + j; const int cnt = (tl + 1) < w ? (tl + 1) : w;
;                 f32x4 sm = r[15 + j];
; #pragma unroll
;                 for (int q = 1; q < 16; ++q) if (q < w) sm += r[15 + j - q];
;                 const f32x4 o = sm * (1.0f / (float)cnt) - r[15 + j];
;                 if (tl >= L - 15) *(f32x4*)(out + O_PPOOL + ((size_t)(((row0 + j) >> 11) * 15 + (tl - (L - 15))) * 512 + c4)) = r[15 + j];
;                 v2u wv; wv.x = cvt_pk_bf16(o[0], o[1]); wv.y = cvt_pk_bf16(o[2], o[3]);
;                 *(v2u*)(AMIX + (size_t)(row0 + j) * D + 512 + c4) = wv;
.LBB0_289:
	s_or_b64 exec, exec, s[14:15]
	s_waitcnt vmcnt(7)
	s_mov_b64 s[56:57], exec
	v_pk_add_f32 v[250:251], v[30:31], v[70:71]
	v_pk_add_f32 v[252:253], v[32:33], v[72:73]
	s_andn2_b64 exec, s[56:57], s[12:13]
	s_cbranch_execz .Lpool_x7
	v_pk_add_f32 v[250:251], v[250:251], v[66:67]
	v_pk_add_f32 v[252:253], v[252:253], v[68:69]
	v_pk_add_f32 v[250:251], v[250:251], v[62:63]
	v_pk_add_f32 v[252:253], v[252:253], v[64:65]
	s_and_b64 exec, s[56:57], s[10:11]
	s_cbranch_execz .Lpool_x7
	v_pk_add_f32 v[250:251], v[250:251], v[54:55]
	v_pk_add_f32 v[252:253], v[252:253], v[56:57]
	v_pk_add_f32 v[250:251], v[250:251], v[50:51]
	v_pk_add_f32 v[252:253], v[252:253], v[52:53]
	v_pk_add_f32 v[250:251], v[250:251], v[46:47]
	v_pk_add_f32 v[252:253], v[252:253], v[48:49]
	v_pk_add_f32 v[250:251], v[250:251], v[42:43]
	v_pk_add_f32 v[252:253], v[252:253], v[44:45]
	s_and_b64 exec, s[56:57], s[8:9]
	s_cbranch_execz .Lpool_x7
	v_pk_add_f32 v[250:251], v[250:251], v[38:39]
	v_pk_add_f32 v[252:253], v[252:253], v[40:41]
	v_pk_add_f32 v[250:251], v[250:251], v[34:35]
	v_pk_add_f32 v[252:253], v[252:253], v[36:37]
	v_pk_add_f32 v[250:251], v[250:251], v[26:27]
	v_pk_add_f32 v[252:253], v[252:253], v[28:29]
	v_pk_add_f32 v[250:251], v[250:251], v[22:23]
	v_pk_add_f32 v[252:253], v[252:253], v[24:25]
	v_pk_add_f32 v[250:251], v[250:251], v[14:15]
	v_pk_add_f32 v[252:253], v[252:253], v[16:17]
	v_pk_add_f32 v[250:251], v[250:251], v[10:11]
	v_pk_add_f32 v[252:253], v[252:253], v[12:13]
	v_pk_add_f32 v[250:251], v[250:251], v[6:7]
	v_pk_add_f32 v[252:253], v[252:253], v[8:9]
	v_pk_add_f32 v[250:251], v[250:251], v[2:3]
	v_pk_add_f32 v[252:253], v[252:253], v[4:5]
.Lpool_x7:
	s_mov_b64 exec, s[56:57]
	v_add_u32_e32 v74, 8, v104
	v_min_u32_e32 v6, v74, v106
	v_cvt_f32_ubyte0_e32 v6, v6
	v_div_scale_f32 v7, s[10:11], v6, v6, 1.0
	v_rcp_f32_e32 v8, v7
	s_nop 0
	v_fma_f32 v9, -v7, v8, 1.0
	v_fmac_f32_e32 v8, v9, v8
	v_div_scale_f32 v9, vcc, 1.0, v6, 1.0
	v_mul_f32_e32 v10, v9, v8
	v_fma_f32 v11, -v7, v10, v9
	v_fmac_f32_e32 v10, v11, v8
	v_fma_f32 v7, -v7, v10, v9
	v_div_fmas_f32 v7, v7, v8, v10
	v_div_fixup_f32 v6, v7, v6, 1.0
	v_xor_b32_e32 v9, 0x80000000, v33
	v_xor_b32_e32 v8, 0x80000000, v32
	v_pk_fma_f32 v[4:5], v[6:7], v[252:253], v[8:9] op_sel_hi:[0,1,1]
	v_pk_fma_f32 v[2:3], v[6:7], v[250:251], v[30:31] op_sel_hi:[0,1,1] neg_lo:[0,0,1] neg_hi:[0,0,1]
	v_cvt_pk_bf16_f32 v2, v2, v3
	v_cvt_pk_bf16_f32 v3, v4, v5
	v_lshl_or_b32 v4, v103, 11, v102
	v_mov_b32_e32 v5, v97
	v_lshl_add_u64 v[4:5], s[16:17], 0, v[4:5]
	v_lshl_add_u64 v[4:5], v[4:5], 0, v[96:97]
	v_add_co_u32_e32 v4, vcc, 0x9440000, v4
	v_lshl_add_u64 v[98:99], v[98:99], 0, s[40:41]
	s_nop 0
	v_addc_co_u32_e32 v5, vcc, 0, v5, vcc
	v_cmp_lt_u64_e32 vcc, s[42:43], v[98:99]
	s_or_b64 s[26:27], vcc, s[26:27]
	v_add_u32_e32 v1, s0, v1
	global_store_dwordx2 v[4:5], v[2:3], off offset:1024
	s_andn2_b64 exec, exec, s[26:27]
	s_cbranch_execz .LBB0_336

; __device__ __forceinline__ unsigned cvt_pk_bf16(float lo, float hi) { unsigned r; asm volatile("v_cvt_pk_bf16_f32 %0, %1, %2" : "=v"(r) : "v"(lo), "v"(hi)); return r; }
; __global__ void __launch_bounds__(512, 2) fwd_kernel(Args a) {
;     ...
;             for (int j = 0; j < 8; ++j) {
;                 const int tl = tl0 + j; const int cnt = (tl + 1) < w ? (tl + 1) : w;
;                 f32x4 sm = r[15 + j];
; #pragma unroll
;                 for (int q = 1; q < 16; ++q) if (q < w) sm += r[15 + j - q];
;                 const f32x4 o = sm * (1.0f / (float)cnt) - r[15 + j];
;                 if (tl >= L - 15) *(f32x4*)(out + O_PPOOL + ((size_t)(((row0 + j) >> 11) * 15 + (tl - (L - 15))) * 512 + c4)) = r[15 + j];
;                 v2u wv; wv.x = cvt_pk_bf16(o[0], o[1]); wv.y = cvt_pk_bf16(o[2], o[3]);
;                 *(v2u*)(AMIX + (size_t)(row0 + j) * D + 512 + c4) = wv;
.LBB0_322:
	s_or_b64 exec, exec, s[8:9]
	s_waitcnt vmcnt(7)
	v_cmp_gt_u32_e64 s[12:13], s4, v112
	v_cmp_lt_u32_e64 s[10:11], s5, v112
	v_lshrrev_b32_e32 v122, 7, v112
	v_cmp_eq_u32_e64 s[8:9], 3, v122
	v_or_b32_e32 v113, 1, v104
	v_lshlrev_b32_e64 v106, v122, 2
	v_min_u32_e32 v115, v113, v106
	v_cvt_f32_ubyte0_e32 v115, v115
	v_div_scale_f32 v118, s[14:15], v115, v115, 1.0
	v_rcp_f32_e32 v119, v118
	s_nop 0
	v_fma_f32 v114, -v118, v119, 1.0
	v_fmac_f32_e32 v119, v114, v119
	v_div_scale_f32 v114, vcc, 1.0, v115, 1.0
	v_mul_f32_e32 v116, v114, v119
	v_fma_f32 v117, -v118, v116, v114
	v_fmac_f32_e32 v116, v117, v119
	v_fma_f32 v114, -v118, v116, v114
	v_div_fmas_f32 v114, v114, v119, v116
	v_div_fixup_f32 v114, v114, v115, 1.0
	v_xor_b32_e32 v117, 0x80000000, v45
	v_xor_b32_e32 v116, 0x80000000, v44
	s_mov_b64 s[56:57], exec
	v_pk_add_f32 v[250:251], v[42:43], v[38:39]
	v_pk_add_f32 v[252:253], v[44:45], v[40:41]
	s_andn2_b64 exec, s[56:57], s[12:13]
	s_cbranch_execz .Lpool_x0
	v_pk_add_f32 v[250:251], v[250:251], v[34:35]
	v_pk_add_f32 v[252:253], v[252:253], v[36:37]
	v_pk_add_f32 v[250:251], v[250:251], v[26:27]
	v_pk_add_f32 v[252:253], v[252:253], v[28:29]
	s_and_b64 exec, s[56:57], s[10:11]
	s_cbranch_execz .Lpool_x0
	v_pk_add_f32 v[250:251], v[250:251], v[22:23]
	v_pk_add_f32 v[252:253], v[252:253], v[24:25]
	v_pk_add_f32 v[250:251], v[250:251], v[14:15]
	v_pk_add_f32 v[252:253], v[252:253], v[16:17]
	v_pk_add_f32 v[250:251], v[250:251], v[10:11]
	v_pk_add_f32 v[252:253], v[252:253], v[12:13]
	v_pk_add_f32 v[250:251], v[250:251], v[6:7]
	v_pk_add_f32 v[252:253], v[252:253], v[8:9]
	s_and_b64 exec, s[56:57], s[8:9]
	s_cbranch_execz .Lpool_x0
	v_pk_add_f32 v[250:251], v[250:251], v[2:3]
	v_pk_add_f32 v[252:253], v[252:253], v[4:5]
	v_pk_add_f32 v[250:251], v[250:251], v[18:19]
	v_pk_add_f32 v[252:253], v[252:253], v[20:21]
	v_pk_add_f32 v[250:251], v[250:251], v[58:59]
	v_pk_add_f32 v[252:253], v[252:253], v[60:61]
	v_pk_add_f32 v[250:251], v[250:251], v[74:75]
	v_pk_add_f32 v[252:253], v[252:253], v[76:77]
	v_pk_add_f32 v[250:251], v[250:251], v[78:79]
	v_pk_add_f32 v[252:253], v[252:253], v[80:81]
	v_pk_add_f32 v[250:251], v[250:251], v[82:83]
	v_pk_add_f32 v[252:253], v[252:253], v[84:85]
	v_pk_add_f32 v[250:251], v[250:251], v[86:87]
	v_pk_add_f32 v[252:253], v[252:253], v[88:89]
	v_pk_add_f32 v[250:251], v[250:251], v[90:91]
	v_pk_add_f32 v[252:253], v[252:253], v[92:93]
.Lpool_x0:
	s_mov_b64 exec, s[56:57]
	v_pk_fma_f32 v[90:91], v[114:115], v[250:251], v[42:43] op_sel_hi:[0,1,1] neg_lo:[0,0,1] neg_hi:[0,0,1]
	v_pk_fma_f32 v[92:93], v[114:115], v[252:253], v[116:117] op_sel_hi:[0,1,1]
	v_cvt_pk_bf16_f32 v114, v90, v91
	v_lshl_add_u64 v[90:91], s[16:17], 0, v[96:97]
	v_lshlrev_b32_e32 v96, 1, v112
	v_cvt_pk_bf16_f32 v115, v92, v93
	v_lshl_add_u64 v[92:93], v[90:91], 0, v[96:97]
	v_add_co_u32_e32 v116, vcc, 0x9440000, v92
	v_cmp_lt_u32_e64 s[14:15], s6, v104
	s_nop 0
	v_addc_co_u32_e32 v117, vcc, 0, v93, vcc
	global_store_dwordx2 v[116:117], v[114:115], off offset:1024
	s_and_saveexec_b64 s[44:45], s[14:15]
	s_cbranch_execz .LBB0_324
	v_add_u32_e32 v112, v108, v113
	v_mov_b32_e32 v113, v97
	v_lshlrev_b64 v[112:113], 11, v[112:113]
	v_lshl_add_u64 v[112:113], v[100:101], 0, v[112:113]
	s_waitcnt vmcnt(7)
	global_store_dwordx4 v[112:113], v[46:49], off
.LBB0_324:
	s_or_b64 exec, exec, s[44:45]
	s_waitcnt vmcnt(7)
	s_mov_b64 s[56:57], exec
	v_pk_add_f32 v[250:251], v[46:47], v[42:43]
	v_pk_add_f32 v[252:253], v[48:49], v[44:45]
	s_andn2_b64 exec, s[56:57], s[12:13]
	s_cbranch_execz .Lpool_x1
	v_pk_add_f32 v[250:251], v[250:251], v[38:39]
	v_pk_add_f32 v[252:253], v[252:253], v[40:41]
	v_pk_add_f32 v[250:251], v[250:251], v[34:35]
	v_pk_add_f32 v[252:253], v[252:253], v[36:37]
	s_and_b64 exec, s[56:57], s[10:11]
	s_cbranch_execz .Lpool_x1
	v_pk_add_f32 v[250:251], v[250:251], v[26:27]
	v_pk_add_f32 v[252:253], v[252:253], v[28:29]
	v_pk_add_f32 v[250:251], v[250:251], v[22:23]
	v_pk_add_f32 v[252:253], v[252:253], v[24:25]
	v_pk_add_f32 v[250:251], v[250:251], v[14:15]
	v_pk_add_f32 v[252:253], v[252:253], v[16:17]
	v_pk_add_f32 v[250:251], v[250:251], v[10:11]
	v_pk_add_f32 v[252:253], v[252:253], v[12:13]
	s_and_b64 exec, s[56:57], s[8:9]
	s_cbranch_execz .Lpool_x1
	v_pk_add_f32 v[250:251], v[250:251], v[6:7]
	v_pk_add_f32 v[252:253], v[252:253], v[8:9]
	v_pk_add_f32 v[250:251], v[250:251], v[2:3]
	v_pk_add_f32 v[252:253], v[252:253], v[4:5]
	v_pk_add_f32 v[250:251], v[250:251], v[18:19]
	v_pk_add_f32 v[252:253], v[252:253], v[20:21]
	v_pk_add_f32 v[250:251], v[250:251], v[58:59]
	v_pk_add_f32 v[252:253], v[252:253], v[60:61]
	v_pk_add_f32 v[250:251], v[250:251], v[74:75]
	v_pk_add_f32 v[252:253], v[252:253], v[76:77]
	v_pk_add_f32 v[250:251], v[250:251], v[78:79]
	v_pk_add_f32 v[252:253], v[252:253], v[80:81]
	v_pk_add_f32 v[250:251], v[250:251], v[82:83]
	v_pk_add_f32 v[252:253], v[252:253], v[84:85]
	v_pk_add_f32 v[250:251], v[250:251], v[86:87]
	v_pk_add_f32 v[252:253], v[252:253], v[88:89]
.Lpool_x1:
	s_mov_b64 exec, s[56:57]
	v_or_b32_e32 v112, 2, v104
	v_min_u32_e32 v113, v112, v106
	v_cvt_f32_ubyte0_e32 v113, v113
	v_div_scale_f32 v115, s[34:35], v113, v113, 1.0
	v_rcp_f32_e32 v118, v115
	s_nop 0
	v_fma_f32 v114, -v115, v118, 1.0
	v_fmac_f32_e32 v118, v114, v118
	v_div_scale_f32 v114, vcc, 1.0, v113, 1.0
	v_mul_f32_e32 v116, v114, v118
	v_fma_f32 v117, -v115, v116, v114
	v_fmac_f32_e32 v116, v117, v118
	v_fma_f32 v114, -v115, v116, v114
	v_div_fmas_f32 v114, v114, v118, v116
	v_div_fixup_f32 v114, v114, v113, 1.0
	v_xor_b32_e32 v117, 0x80000000, v49
	v_xor_b32_e32 v116, 0x80000000, v48
	v_pk_fma_f32 v[88:89], v[114:115], v[252:253], v[116:117] op_sel_hi:[0,1,1]
	v_pk_fma_f32 v[86:87], v[114:115], v[250:251], v[46:47] op_sel_hi:[0,1,1] neg_lo:[0,0,1] neg_hi:[0,0,1]
	v_cvt_pk_bf16_f32 v86, v86, v87
	v_cvt_pk_bf16_f32 v87, v88, v89
	v_add_co_u32_e32 v88, vcc, 0x9440000, v92
	s_nop 1
	v_addc_co_u32_e32 v89, vcc, 0, v93, vcc
	global_store_dwordx2 v[88:89], v[86:87], off offset:3072
	s_and_saveexec_b64 s[44:45], s[14:15]
	s_cbranch_execz .LBB0_326
	v_add_u32_e32 v86, v108, v112
	v_mov_b32_e32 v87, v97
	v_lshlrev_b64 v[86:87], 11, v[86:87]
	v_lshl_add_u64 v[86:87], v[100:101], 0, v[86:87]
	s_waitcnt vmcnt(7)
	global_store_dwordx4 v[86:87], v[50:53], off
; __device__ __forceinline__ unsigned cvt_pk_bf16(float lo, float hi) { unsigned r; asm volatile("v_cvt_pk_bf16_f32 %0, %1, %2" : "=v"(r) : "v"(lo), "v"(hi)); return r; }
; __global__ void __launch_bounds__(512, 2) fwd_kernel(Args a) {
;     ...
;             for (int j = 0; j < 8; ++j) {
;                 const int tl = tl0 + j; const int cnt = (tl + 1) < w ? (tl + 1) : w;
;                 f32x4 sm = r[15 + j];
; #pragma unroll
;                 for (int q = 1; q < 16; ++q) if (q < w) sm += r[15 + j - q];
;                 const f32x4 o = sm * (1.0f / (float)cnt) - r[15 + j];
;                 if (tl >= L - 15) *(f32x4*)(out + O_PPOOL + ((size_t)(((row0 + j) >> 11) * 15 + (tl - (L - 15))) * 512 + c4)) = r[15 + j];
;                 v2u wv; wv.x = cvt_pk_bf16(o[0], o[1]); wv.y = cvt_pk_bf16(o[2], o[3]);
;                 *(v2u*)(AMIX + (size_t)(row0 + j) * D + 512 + c4) = wv;
.LBB0_326:
	s_or_b64 exec, exec, s[44:45]
	s_waitcnt vmcnt(7)
	s_mov_b64 s[56:57], exec
	v_pk_add_f32 v[250:251], v[50:51], v[46:47]
	v_pk_add_f32 v[252:253], v[52:53], v[48:49]
	s_andn2_b64 exec, s[56:57], s[12:13]
	s_cbranch_execz .Lpool_x2
	v_pk_add_f32 v[250:251], v[250:251], v[42:43]
	v_pk_add_f32 v[252:253], v[252:253], v[44:45]
	v_pk_add_f32 v[250:251], v[250:251], v[38:39]
	v_pk_add_f32 v[252:253], v[252:253], v[40:41]
	s_and_b64 exec, s[56:57], s[10:11]
	s_cbranch_execz .Lpool_x2
	v_pk_add_f32 v[250:251], v[250:251], v[34:35]
	v_pk_add_f32 v[252:253], v[252:253], v[36:37]
	v_pk_add_f32 v[250:251], v[250:251], v[26:27]
	v_pk_add_f32 v[252:253], v[252:253], v[28:29]
	v_pk_add_f32 v[250:251], v[250:251], v[22:23]
	v_pk_add_f32 v[252:253], v[252:253], v[24:25]
	v_pk_add_f32 v[250:251], v[250:251], v[14:15]
	v_pk_add_f32 v[252:253], v[252:253], v[16:17]
	s_and_b64 exec, s[56:57], s[8:9]
	s_cbranch_execz .Lpool_x2
	v_pk_add_f32 v[250:251], v[250:251], v[10:11]
	v_pk_add_f32 v[252:253], v[252:253], v[12:13]
	v_pk_add_f32 v[250:251], v[250:251], v[6:7]
	v_pk_add_f32 v[252:253], v[252:253], v[8:9]
	v_pk_add_f32 v[250:251], v[250:251], v[2:3]
	v_pk_add_f32 v[252:253], v[252:253], v[4:5]
	v_pk_add_f32 v[250:251], v[250:251], v[18:19]
	v_pk_add_f32 v[252:253], v[252:253], v[20:21]
	v_pk_add_f32 v[250:251], v[250:251], v[58:59]
	v_pk_add_f32 v[252:253], v[252:253], v[60:61]
	v_pk_add_f32 v[250:251], v[250:251], v[74:75]
	v_pk_add_f32 v[252:253], v[252:253], v[76:77]
	v_pk_add_f32 v[250:251], v[250:251], v[78:79]
	v_pk_add_f32 v[252:253], v[252:253], v[80:81]
	v_pk_add_f32 v[250:251], v[250:251], v[82:83]
	v_pk_add_f32 v[252:253], v[252:253], v[84:85]
.Lpool_x2:
	s_mov_b64 exec, s[56:57]
	v_min_u32_e32 v87, v111, v106
	v_cvt_f32_ubyte0_e32 v87, v87
	v_div_scale_f32 v92, s[34:35], v87, v87, 1.0
	v_rcp_f32_e32 v93, v92
	s_nop 0
	v_fma_f32 v86, -v92, v93, 1.0
	v_fmac_f32_e32 v93, v86, v93
	v_div_scale_f32 v86, vcc, 1.0, v87, 1.0
	v_mul_f32_e32 v88, v86, v93
	v_fma_f32 v89, -v92, v88, v86
	v_fmac_f32_e32 v88, v89, v93
	v_fma_f32 v86, -v92, v88, v86
	v_div_fmas_f32 v86, v86, v93, v88
	v_div_fixup_f32 v86, v86, v87, 1.0
	v_xor_b32_e32 v89, 0x80000000, v53
	v_xor_b32_e32 v88, 0x80000000, v52
	v_pk_fma_f32 v[82:83], v[86:87], v[250:251], v[50:51] op_sel_hi:[0,1,1] neg_lo:[0,0,1] neg_hi:[0,0,1]
	v_pk_fma_f32 v[84:85], v[86:87], v[252:253], v[88:89] op_sel_hi:[0,1,1]
	v_cvt_pk_bf16_f32 v86, v82, v83
	v_lshl_add_u64 v[82:83], v[90:91], 0, v[96:97]
	v_cvt_pk_bf16_f32 v87, v84, v85
	v_add_co_u32_e32 v84, vcc, 0x9441000, v82
	s_nop 1
	v_addc_co_u32_e32 v85, vcc, 0, v83, vcc
	v_cmp_lt_u32_e32 vcc, s1, v111
	global_store_dwordx2 v[84:85], v[86:87], off offset:1024
	s_and_saveexec_b64 s[44:45], vcc
	s_cbranch_execz .LBB0_328
	v_add_u32_e32 v84, v108, v111
	v_mov_b32_e32 v85, v97
	v_lshlrev_b64 v[84:85], 11, v[84:85]
	v_lshl_add_u64 v[84:85], v[100:101], 0, v[84:85]
	s_waitcnt vmcnt(7)
	global_store_dwordx4 v[84:85], v[54:57], off
.LBB0_328:
	s_or_b64 exec, exec, s[44:45]
	s_waitcnt vmcnt(7)
	s_mov_b64 s[56:57], exec
	v_pk_add_f32 v[250:251], v[54:55], v[50:51]
	v_pk_add_f32 v[252:253], v[56:57], v[52:53]
	s_andn2_b64 exec, s[56:57], s[12:13]
	s_cbranch_execz .Lpool_x3
	v_pk_add_f32 v[250:251], v[250:251], v[46:47]
	v_pk_add_f32 v[252:253], v[252:253], v[48:49]
	v_pk_add_f32 v[250:251], v[250:251], v[42:43]
	v_pk_add_f32 v[252:253], v[252:253], v[44:45]
	s_and_b64 exec, s[56:57], s[10:11]
	s_cbranch_execz .Lpool_x3
	v_pk_add_f32 v[250:251], v[250:251], v[38:39]
	v_pk_add_f32 v[252:253], v[252:253], v[40:41]
	v_pk_add_f32 v[250:251], v[250:251], v[34:35]
	v_pk_add_f32 v[252:253], v[252:253], v[36:37]
	v_pk_add_f32 v[250:251], v[250:251], v[26:27]
	v_pk_add_f32 v[252:253], v[252:253], v[28:29]
	v_pk_add_f32 v[250:251], v[250:251], v[22:23]
	v_pk_add_f32 v[252:253], v[252:253], v[24:25]
	s_and_b64 exec, s[56:57], s[8:9]
	s_cbranch_execz .Lpool_x3
	v_pk_add_f32 v[250:251], v[250:251], v[14:15]
	v_pk_add_f32 v[252:253], v[252:253], v[16:17]
	v_pk_add_f32 v[250:251], v[250:251], v[10:11]
	v_pk_add_f32 v[252:253], v[252:253], v[12:13]
	v_pk_add_f32 v[250:251], v[250:251], v[6:7]
	v_pk_add_f32 v[252:253], v[252:253], v[8:9]
	v_pk_add_f32 v[250:251], v[250:251], v[2:3]
	v_pk_add_f32 v[252:253], v[252:253], v[4:5]
	v_pk_add_f32 v[250:251], v[250:251], v[18:19]
	v_pk_add_f32 v[252:253], v[252:253], v[20:21]
	v_pk_add_f32 v[250:251], v[250:251], v[58:59]
	v_pk_add_f32 v[252:253], v[252:253], v[60:61]
	v_pk_add_f32 v[250:251], v[250:251], v[74:75]
	v_pk_add_f32 v[252:253], v[252:253], v[76:77]
	v_pk_add_f32 v[250:251], v[250:251], v[78:79]
	v_pk_add_f32 v[252:253], v[252:253], v[80:81]
.Lpool_x3:
	s_mov_b64 exec, s[56:57]
	v_min_u32_e32 v85, v110, v106
	v_cvt_f32_ubyte0_e32 v85, v85
	v_div_scale_f32 v88, s[34:35], v85, v85, 1.0
	v_rcp_f32_e32 v89, v88
	s_nop 0
	v_fma_f32 v84, -v88, v89, 1.0
	v_fmac_f32_e32 v89, v84, v89
	v_div_scale_f32 v84, vcc, 1.0, v85, 1.0
	v_mul_f32_e32 v86, v84, v89
	v_fma_f32 v87, -v88, v86, v84
	v_fmac_f32_e32 v86, v87, v89
	v_fma_f32 v84, -v88, v86, v84
	v_div_fmas_f32 v84, v84, v89, v86
	v_div_fixup_f32 v84, v84, v85, 1.0
	v_xor_b32_e32 v87, 0x80000000, v57
	v_xor_b32_e32 v86, 0x80000000, v56
	v_pk_fma_f32 v[80:81], v[84:85], v[252:253], v[86:87] op_sel_hi:[0,1,1]
	v_pk_fma_f32 v[78:79], v[84:85], v[250:251], v[54:55] op_sel_hi:[0,1,1] neg_lo:[0,0,1] neg_hi:[0,0,1]
	v_cvt_pk_bf16_f32 v78, v78, v79
	v_cvt_pk_bf16_f32 v79, v80, v81
	v_add_co_u32_e32 v80, vcc, 0x9441000, v82
	s_nop 1
	v_addc_co_u32_e32 v81, vcc, 0, v83, vcc
	global_store_dwordx2 v[80:81], v[78:79], off offset:3072
	s_and_saveexec_b64 s[44:45], s[14:15]
	s_cbranch_execz .LBB0_330
	v_add_u32_e32 v78, v108, v110
	v_mov_b32_e32 v79, v97
	v_lshlrev_b64 v[78:79], 11, v[78:79]
	v_lshl_add_u64 v[78:79], v[100:101], 0, v[78:79]
	s_waitcnt vmcnt(7)
	global_store_dwordx4 v[78:79], v[62:65], off
; __device__ __forceinline__ unsigned cvt_pk_bf16(float lo, float hi) { unsigned r; asm volatile("v_cvt_pk_bf16_f32 %0, %1, %2" : "=v"(r) : "v"(lo), "v"(hi)); return r; }
; __global__ void __launch_bounds__(512, 2) fwd_kernel(Args a) {
;     ...
;             for (int j = 0; j < 8; ++j) {
;                 const int tl = tl0 + j; const int cnt = (tl + 1) < w ? (tl + 1) : w;
;                 f32x4 sm = r[15 + j];
; #pragma unroll
;                 for (int q = 1; q < 16; ++q) if (q < w) sm += r[15 + j - q];
;                 const f32x4 o = sm * (1.0f / (float)cnt) - r[15 + j];
;                 if (tl >= L - 15) *(f32x4*)(out + O_PPOOL + ((size_t)(((row0 + j) >> 11) * 15 + (tl - (L - 15))) * 512 + c4)) = r[15 + j];
;                 v2u wv; wv.x = cvt_pk_bf16(o[0], o[1]); wv.y = cvt_pk_bf16(o[2], o[3]);
;                 *(v2u*)(AMIX + (size_t)(row0 + j) * D + 512 + c4) = wv;
.LBB0_330:
	s_or_b64 exec, exec, s[44:45]
	s_waitcnt vmcnt(7)
	s_mov_b64 s[56:57], exec
	v_pk_add_f32 v[250:251], v[62:63], v[54:55]
	v_pk_add_f32 v[252:253], v[64:65], v[56:57]
	s_andn2_b64 exec, s[56:57], s[12:13]
	s_cbranch_execz .Lpool_x4
	v_pk_add_f32 v[250:251], v[250:251], v[50:51]
	v_pk_add_f32 v[252:253], v[252:253], v[52:53]
	v_pk_add_f32 v[250:251], v[250:251], v[46:47]
	v_pk_add_f32 v[252:253], v[252:253], v[48:49]
	s_and_b64 exec, s[56:57], s[10:11]
	s_cbranch_execz .Lpool_x4
	v_pk_add_f32 v[250:251], v[250:251], v[42:43]
	v_pk_add_f32 v[252:253], v[252:253], v[44:45]
	v_pk_add_f32 v[250:251], v[250:251], v[38:39]
	v_pk_add_f32 v[252:253], v[252:253], v[40:41]
	v_pk_add_f32 v[250:251], v[250:251], v[34:35]
	v_pk_add_f32 v[252:253], v[252:253], v[36:37]
	v_pk_add_f32 v[250:251], v[250:251], v[26:27]
	v_pk_add_f32 v[252:253], v[252:253], v[28:29]
	s_and_b64 exec, s[56:57], s[8:9]
	s_cbranch_execz .Lpool_x4
	v_pk_add_f32 v[250:251], v[250:251], v[22:23]
	v_pk_add_f32 v[252:253], v[252:253], v[24:25]
	v_pk_add_f32 v[250:251], v[250:251], v[14:15]
	v_pk_add_f32 v[252:253], v[252:253], v[16:17]
	v_pk_add_f32 v[250:251], v[250:251], v[10:11]
	v_pk_add_f32 v[252:253], v[252:253], v[12:13]
	v_pk_add_f32 v[250:251], v[250:251], v[6:7]
	v_pk_add_f32 v[252:253], v[252:253], v[8:9]
	v_pk_add_f32 v[250:251], v[250:251], v[2:3]
	v_pk_add_f32 v[252:253], v[252:253], v[4:5]
	v_pk_add_f32 v[250:251], v[250:251], v[18:19]
	v_pk_add_f32 v[252:253], v[252:253], v[20:21]
	v_pk_add_f32 v[250:251], v[250:251], v[58:59]
	v_pk_add_f32 v[252:253], v[252:253], v[60:61]
	v_pk_add_f32 v[250:251], v[250:251], v[74:75]
	v_pk_add_f32 v[252:253], v[252:253], v[76:77]
.Lpool_x4:
	s_mov_b64 exec, s[56:57]
	v_min_u32_e32 v79, v109, v106
	v_cvt_f32_ubyte0_e32 v79, v79
	v_div_scale_f32 v82, s[14:15], v79, v79, 1.0
	v_rcp_f32_e32 v83, v82
	s_nop 0
	v_fma_f32 v78, -v82, v83, 1.0
	v_fmac_f32_e32 v83, v78, v83
	v_div_scale_f32 v78, vcc, 1.0, v79, 1.0
	v_mul_f32_e32 v80, v78, v83
	v_fma_f32 v81, -v82, v80, v78
	v_fmac_f32_e32 v80, v81, v83
	v_fma_f32 v78, -v82, v80, v78
	v_div_fmas_f32 v78, v78, v83, v80
	v_div_fixup_f32 v78, v78, v79, 1.0
	v_xor_b32_e32 v81, 0x80000000, v65
	v_xor_b32_e32 v80, 0x80000000, v64
	v_pk_fma_f32 v[74:75], v[78:79], v[250:251], v[62:63] op_sel_hi:[0,1,1] neg_lo:[0,0,1] neg_hi:[0,0,1]
	v_pk_fma_f32 v[76:77], v[78:79], v[252:253], v[80:81] op_sel_hi:[0,1,1]
	v_cvt_pk_bf16_f32 v78, v74, v75
	v_lshl_add_u64 v[74:75], v[90:91], 0, v[96:97]
	v_cvt_pk_bf16_f32 v79, v76, v77
	v_add_co_u32_e32 v76, vcc, 0x9442000, v74
	s_nop 1
	v_addc_co_u32_e32 v77, vcc, 0, v75, vcc
	v_cmp_lt_u32_e32 vcc, s1, v109
	global_store_dwordx2 v[76:77], v[78:79], off offset:1024
	s_and_saveexec_b64 s[14:15], vcc
	s_cbranch_execz .LBB0_332
	v_add_u32_e32 v76, v108, v109
	v_mov_b32_e32 v77, v97
	v_lshlrev_b64 v[76:77], 11, v[76:77]
	v_lshl_add_u64 v[76:77], v[100:101], 0, v[76:77]
	s_waitcnt vmcnt(7)
	global_store_dwordx4 v[76:77], v[66:69], off
.LBB0_332:
	s_or_b64 exec, exec, s[14:15]
	s_waitcnt vmcnt(7)
	s_mov_b64 s[56:57], exec
	v_pk_add_f32 v[250:251], v[66:67], v[62:63]
	v_pk_add_f32 v[252:253], v[68:69], v[64:65]
	s_andn2_b64 exec, s[56:57], s[12:13]
	s_cbranch_execz .Lpool_x5
	v_pk_add_f32 v[250:251], v[250:251], v[54:55]
	v_pk_add_f32 v[252:253], v[252:253], v[56:57]
	v_pk_add_f32 v[250:251], v[250:251], v[50:51]
	v_pk_add_f32 v[252:253], v[252:253], v[52:53]
	s_and_b64 exec, s[56:57], s[10:11]
	s_cbranch_execz .Lpool_x5
	v_pk_add_f32 v[250:251], v[250:251], v[46:47]
	v_pk_add_f32 v[252:253], v[252:253], v[48:49]
	v_pk_add_f32 v[250:251], v[250:251], v[42:43]
	v_pk_add_f32 v[252:253], v[252:253], v[44:45]
	v_pk_add_f32 v[250:251], v[250:251], v[38:39]
	v_pk_add_f32 v[252:253], v[252:253], v[40:41]
	v_pk_add_f32 v[250:251], v[250:251], v[34:35]
	v_pk_add_f32 v[252:253], v[252:253], v[36:37]
	s_and_b64 exec, s[56:57], s[8:9]
	s_cbranch_execz .Lpool_x5
	v_pk_add_f32 v[250:251], v[250:251], v[26:27]
	v_pk_add_f32 v[252:253], v[252:253], v[28:29]
	v_pk_add_f32 v[250:251], v[250:251], v[22:23]
	v_pk_add_f32 v[252:253], v[252:253], v[24:25]
	v_pk_add_f32 v[250:251], v[250:251], v[14:15]
	v_pk_add_f32 v[252:253], v[252:253], v[16:17]
	v_pk_add_f32 v[250:251], v[250:251], v[10:11]
	v_pk_add_f32 v[252:253], v[252:253], v[12:13]
	v_pk_add_f32 v[250:251], v[250:251], v[6:7]
	v_pk_add_f32 v[252:253], v[252:253], v[8:9]
	v_pk_add_f32 v[250:251], v[250:251], v[2:3]
	v_pk_add_f32 v[252:253], v[252:253], v[4:5]
	v_pk_add_f32 v[250:251], v[250:251], v[18:19]
	v_pk_add_f32 v[252:253], v[252:253], v[20:21]
	v_pk_add_f32 v[250:251], v[250:251], v[58:59]
	v_pk_add_f32 v[252:253], v[252:253], v[60:61]
; __device__ __forceinline__ unsigned cvt_pk_bf16(float lo, float hi) { unsigned r; asm volatile("v_cvt_pk_bf16_f32 %0, %1, %2" : "=v"(r) : "v"(lo), "v"(hi)); return r; }
; __global__ void __launch_bounds__(512, 2) fwd_kernel(Args a) {
;     ...
;             for (int j = 0; j < 8; ++j) {
;                 const int tl = tl0 + j; const int cnt = (tl + 1) < w ? (tl + 1) : w;
;                 f32x4 sm = r[15 + j];
; #pragma unroll
;                 for (int q = 1; q < 16; ++q) if (q < w) sm += r[15 + j - q];
;                 const f32x4 o = sm * (1.0f / (float)cnt) - r[15 + j];
;                 if (tl >= L - 15) *(f32x4*)(out + O_PPOOL + ((size_t)(((row0 + j) >> 11) * 15 + (tl - (L - 15))) * 512 + c4)) = r[15 + j];
;                 v2u wv; wv.x = cvt_pk_bf16(o[0], o[1]); wv.y = cvt_pk_bf16(o[2], o[3]);
;                 *(v2u*)(AMIX + (size_t)(row0 + j) * D + 512 + c4) = wv;
.Lpool_x5:
	s_mov_b64 exec, s[56:57]
	v_min_u32_e32 v77, v107, v106
	v_cvt_f32_ubyte0_e32 v77, v77
	v_div_scale_f32 v80, s[14:15], v77, v77, 1.0
	v_rcp_f32_e32 v81, v80
	s_nop 0
	v_fma_f32 v76, -v80, v81, 1.0
	v_fmac_f32_e32 v81, v76, v81
	v_div_scale_f32 v76, vcc, 1.0, v77, 1.0
	v_mul_f32_e32 v78, v76, v81
	v_fma_f32 v79, -v80, v78, v76
	v_fmac_f32_e32 v78, v79, v81
	v_fma_f32 v76, -v80, v78, v76
	v_div_fmas_f32 v76, v76, v81, v78
	v_div_fixup_f32 v76, v76, v77, 1.0
	v_xor_b32_e32 v79, 0x80000000, v69
	v_xor_b32_e32 v78, 0x80000000, v68
	v_pk_fma_f32 v[60:61], v[76:77], v[252:253], v[78:79] op_sel_hi:[0,1,1]
	v_pk_fma_f32 v[58:59], v[76:77], v[250:251], v[66:67] op_sel_hi:[0,1,1] neg_lo:[0,0,1] neg_hi:[0,0,1]
	v_cvt_pk_bf16_f32 v58, v58, v59
	v_cvt_pk_bf16_f32 v59, v60, v61
	v_add_co_u32_e32 v60, vcc, 0x9442000, v74
	s_nop 1
	v_addc_co_u32_e32 v61, vcc, 0, v75, vcc
	v_cmp_lt_u32_e32 vcc, s1, v107
	global_store_dwordx2 v[60:61], v[58:59], off offset:3072
	s_and_saveexec_b64 s[14:15], vcc
	s_cbranch_execz .LBB0_334
	v_add_u32_e32 v58, v108, v107
	v_mov_b32_e32 v59, v97
	v_lshlrev_b64 v[58:59], 11, v[58:59]
	v_lshl_add_u64 v[58:59], v[100:101], 0, v[58:59]
	s_waitcnt vmcnt(7)
	global_store_dwordx4 v[58:59], v[70:73], off
.LBB0_334:
	s_or_b64 exec, exec, s[14:15]
	s_waitcnt vmcnt(7)
	s_mov_b64 s[56:57], exec
	v_pk_add_f32 v[250:251], v[70:71], v[66:67]
	v_pk_add_f32 v[252:253], v[72:73], v[68:69]
	s_andn2_b64 exec, s[56:57], s[12:13]
	s_cbranch_execz .Lpool_x6
	v_pk_add_f32 v[250:251], v[250:251], v[62:63]
	v_pk_add_f32 v[252:253], v[252:253], v[64:65]
	v_pk_add_f32 v[250:251], v[250:251], v[54:55]
	v_pk_add_f32 v[252:253], v[252:253], v[56:57]
	s_and_b64 exec, s[56:57], s[10:11]
	s_cbranch_execz .Lpool_x6
	v_pk_add_f32 v[250:251], v[250:251], v[50:51]
	v_pk_add_f32 v[252:253], v[252:253], v[52:53]
	v_pk_add_f32 v[250:251], v[250:251], v[46:47]
	v_pk_add_f32 v[252:253], v[252:253], v[48:49]
	v_pk_add_f32 v[250:251], v[250:251], v[42:43]
	v_pk_add_f32 v[252:253], v[252:253], v[44:45]
	v_pk_add_f32 v[250:251], v[250:251], v[38:39]
	v_pk_add_f32 v[252:253], v[252:253], v[40:41]
	s_and_b64 exec, s[56:57], s[8:9]
	s_cbranch_execz .Lpool_x6
	v_pk_add_f32 v[250:251], v[250:251], v[34:35]
	v_pk_add_f32 v[252:253], v[252:253], v[36:37]
	v_pk_add_f32 v[250:251], v[250:251], v[26:27]
	v_pk_add_f32 v[252:253], v[252:253], v[28:29]
	v_pk_add_f32 v[250:251], v[250:251], v[22:23]
	v_pk_add_f32 v[252:253], v[252:253], v[24:25]
	v_pk_add_f32 v[250:251], v[250:251], v[14:15]
	v_pk_add_f32 v[252:253], v[252:253], v[16:17]
	v_pk_add_f32 v[250:251], v[250:251], v[10:11]
	v_pk_add_f32 v[252:253], v[252:253], v[12:13]
	v_pk_add_f32 v[250:251], v[250:251], v[6:7]
	v_pk_add_f32 v[252:253], v[252:253], v[8:9]
	v_pk_add_f32 v[250:251], v[250:251], v[2:3]
	v_pk_add_f32 v[252:253], v[252:253], v[4:5]
	v_pk_add_f32 v[250:251], v[250:251], v[18:19]
	v_pk_add_f32 v[252:253], v[252:253], v[20:21]
.Lpool_x6:
	s_mov_b64 exec, s[56:57]
	v_min_u32_e32 v59, v105, v106
	v_cvt_f32_ubyte0_e32 v59, v59
	v_div_scale_f32 v74, s[14:15], v59, v59, 1.0
	v_rcp_f32_e32 v75, v74
	s_nop 0
	v_fma_f32 v58, -v74, v75, 1.0
	v_fmac_f32_e32 v75, v58, v75
	v_div_scale_f32 v58, vcc, 1.0, v59, 1.0
	v_mul_f32_e32 v60, v58, v75
	v_fma_f32 v61, -v74, v60, v58
	v_fmac_f32_e32 v60, v61, v75
	v_fma_f32 v58, -v74, v60, v58
	v_div_fmas_f32 v58, v58, v75, v60
	v_div_fixup_f32 v58, v58, v59, 1.0
	v_xor_b32_e32 v61, 0x80000000, v73
	v_xor_b32_e32 v60, 0x80000000, v72
	v_pk_fma_f32 v[20:21], v[58:59], v[252:253], v[60:61] op_sel_hi:[0,1,1]
	v_pk_fma_f32 v[18:19], v[58:59], v[250:251], v[70:71] op_sel_hi:[0,1,1] neg_lo:[0,0,1] neg_hi:[0,0,1]
	v_cvt_pk_bf16_f32 v18, v18, v19
	v_cvt_pk_bf16_f32 v19, v20, v21
	v_lshl_add_u64 v[20:21], v[90:91], 0, v[96:97]
	v_add_co_u32_e32 v20, vcc, 0x9443000, v20
	s_nop 1
	v_addc_co_u32_e32 v21, vcc, 0, v21, vcc
	v_cmp_lt_u32_e32 vcc, s1, v105
	global_store_dwordx2 v[20:21], v[18:19], off offset:1024
	s_and_saveexec_b64 s[14:15], vcc
	s_cbranch_execz .LBB0_289
	v_add_u32_e32 v18, v108, v105
	v_mov_b32_e32 v19, v97
	v_lshlrev_b64 v[18:19], 11, v[18:19]
	v_lshl_add_u64 v[18:19], v[100:101], 0, v[18:19]
	s_waitcnt vmcnt(7)
	global_store_dwordx4 v[18:19], v[30:33], off
	s_branch .LBB0_289
